# phase-0 weight transpose loop hand-written: 16-byte loads, next item's loads in flight during the LDS transpose (counted vmcnt), items dealt unevenly so workgroups that also run adaLN take fewer
# speedup vs baseline: 1.0193x; 1.0104x over previous
.LBB0_29:
	s_lshr_b32 s94, s93, 6
	s_lshl_b32 s0, s24, 3
	s_add_i32 s8, s0, s94
	s_lshl_b32 s3, s56, 3
	s_lshl_b32 s66, s56, 9
	s_add_u32 s6, s54, 0x500000
	s_addc_u32 s7, s55, 0
	s_add_u32 s64, s54, 0x900000
	s_addc_u32 s65, s55, 0
	s_add_u32 s60, s54, 0xb00000
	s_addc_u32 s61, s55, 0
	s_add_u32 s50, s54, 0x1300000
	s_addc_u32 s51, s55, 0
	s_cmp_lt_i32 s40, 1
	v_writelane_b32 v246, s24, 6
	s_cselect_b64 s[4:5], -1, 0
	s_cmp_gt_i32 s40, 0
	v_writelane_b32 v246, s0, 7
	s_cselect_b64 s[0:1], -1, 0
	s_cmp_lt_i32 s41, 1
	s_cselect_b64 s[10:11], -1, 0
	s_or_b64 s[0:1], s[10:11], s[0:1]
	s_and_b64 vcc, exec, s[0:1]
	s_cbranch_vccnz .LBB0_71
	v_mov_b32_e32 v1, 0
	v_mbcnt_lo_u32_b32 v163, -1, 0
	v_mbcnt_hi_u32_b32 v163, -1, v163
	global_load_dwordx2 v[2:3], v1, s[96:97] offset:112 sc0
	global_load_dwordx2 v[4:5], v1, s[96:97] offset:144 sc0
	global_load_dwordx2 v[6:7], v1, s[96:97] offset:96 sc0
	global_load_dwordx2 v[8:9], v1, s[96:97] offset:104 sc0
	s_cmpk_gt_i32 s8, 0x14ff
	s_waitcnt vmcnt(3)
	v_readfirstlane_b32 s13, v3
	v_readfirstlane_b32 s12, v2
	s_waitcnt vmcnt(2)
	v_readfirstlane_b32 s11, v5
	v_readfirstlane_b32 s10, v4
	s_waitcnt vmcnt(1)
	v_readfirstlane_b32 s15, v7
	v_readfirstlane_b32 s14, v6
	s_waitcnt vmcnt(0)
	v_readfirstlane_b32 s17, v9
	v_readfirstlane_b32 s16, v8
	v_lshrrev_b32_e32 v3, 3, v163
	v_and_b32_e32 v2, 7, v163
	v_lshlrev_b32_e32 v4, 4, v2
	s_lshl_b32 s18, s94, 14
	v_mul_u32_u24_e32 v5, 33, v3
	v_lshl_add_u32 v5, v2, 2, v5
	v_lshl_add_u32 v5, v5, 2, s18
	v_mul_u32_u24_e32 v6, 0x108, v2
	v_add_u32_e32 v6, v6, v3
	v_lshl_add_u32 v6, v6, 2, s18
	s_lshr_b32 s18, s8, 3
	s_cmp_lg_u32 s56, 0x100
	s_cbranch_scc1 .Ltr_generic
	s_cmp_lt_u32 s18, 0xc0
	s_cbranch_scc0 .Ltr_free
	s_mul_i32 s0, s18, 13
	s_add_i32 s9, s0, 13
	s_branch .Ltr_dealt
.Ltr_free:
	s_sub_i32 s18, s18, 0xc0
	s_mul_i32 s0, s18, 46
	s_addk_i32 s0, 0x9c0
	s_add_i32 s9, s0, 46
.Ltr_dealt:
	s_add_i32 s0, s0, s94
	s_mov_b32 s1, 8
	s_branch .Ltr_range
.Ltr_generic:
	s_mov_b32 s0, s8
	s_mov_b32 s1, s3
	s_movk_i32 s9, 0x1500
.Ltr_range:
	s_min_u32 s9, s9, 0x1500
	s_cmp_lt_u32 s0, s9
	s_cbranch_scc0 .Ltr_done
	s_cmpk_lt_u32 s0, 0x400
	s_cbranch_scc0 .Ltr_c1_p
	v_mov_b32_e32 v30, s0
	v_mov_b32_e32 v24, s12
	v_mov_b32_e32 v25, s13
	v_mov_b32_e32 v26, 6
	v_mov_b32_e32 v27, 11
	v_mov_b32_e32 v28, s6
	v_mov_b32_e32 v29, s7
	s_branch .Ltr_go_p
.Ltr_c1_p:
	s_cmpk_lt_u32 s0, 0x500
	s_cbranch_scc0 .Ltr_c2_p
	s_sub_i32 s18, s0, 0x400
	v_mov_b32_e32 v30, s18
	s_add_u32 s18, s10, 0x200000
	s_addc_u32 s19, s11, 0
	v_mov_b32_e32 v24, s18
	v_mov_b32_e32 v25, s19
	v_mov_b32_e32 v26, 5
	v_mov_b32_e32 v27, 11
	s_add_u32 s18, s54, 0x900400
	s_addc_u32 s19, s55, 0
	v_mov_b32_e32 v28, s18
	v_mov_b32_e32 v29, s19
	s_branch .Ltr_go_p
.Ltr_c2_p:
	s_cmpk_lt_u32 s0, 0xd00
	s_cbranch_scc0 .Ltr_c3_p
	s_sub_i32 s18, s0, 0x500
	v_mov_b32_e32 v30, s18
	v_mov_b32_e32 v24, s14
	v_mov_b32_e32 v25, s15
	v_mov_b32_e32 v26, 7
	v_mov_b32_e32 v27, 11
	v_mov_b32_e32 v28, s60
	v_mov_b32_e32 v29, s61
	s_branch .Ltr_go_p
.Ltr_c3_p:
	s_sub_i32 s18, s0, 0xd00
	v_mov_b32_e32 v30, s18
	v_mov_b32_e32 v24, s16
	v_mov_b32_e32 v25, s17
	v_mov_b32_e32 v26, 5
	v_mov_b32_e32 v27, 13
	v_mov_b32_e32 v28, s50
	v_mov_b32_e32 v29, s51
.Ltr_go_p:
	v_lshrrev_b32_e32 v31, v26, v30
	v_lshlrev_b32_e32 v20, v26, v31
	v_sub_u32_e32 v20, v30, v20
	v_add_u32_e32 v21, 13, v26
	v_lshlrev_b32_e32 v21, v21, v31
	v_lshl_add_u32 v21, v20, 7, v21
	v_add_u32_e32 v22, 7, v26
	v_lshlrev_b32_e32 v23, v22, v3
	v_add3_u32 v21, v21, v23, v4
	v_add_co_u32_e32 v20, vcc, v24, v21
	s_nop 1
	v_addc_co_u32_e32 v21, vcc, 0, v25, vcc
	v_add_u32_e32 v22, 3, v22
	v_lshlrev_b32_e64 v22, v22, 1
	v_mov_b32_e32 v23, 0
	global_load_dwordx4 v[32:35], v[20:21], off
	v_lshl_add_u64 v[20:21], v[20:21], 0, v[22:23]
	global_load_dwordx4 v[36:39], v[20:21], off
	v_lshl_add_u64 v[20:21], v[20:21], 0, v[22:23]
	global_load_dwordx4 v[40:43], v[20:21], off
	v_lshl_add_u64 v[20:21], v[20:21], 0, v[22:23]
	global_load_dwordx4 v[44:47], v[20:21], off
	v_lshl_add_u64 v[20:21], v[20:21], 0, v[22:23]
	global_load_dwordx4 v[48:51], v[20:21], off
	v_lshl_add_u64 v[20:21], v[20:21], 0, v[22:23]
	global_load_dwordx4 v[52:55], v[20:21], off
	v_lshl_add_u64 v[20:21], v[20:21], 0, v[22:23]
	global_load_dwordx4 v[56:59], v[20:21], off
	v_lshl_add_u64 v[20:21], v[20:21], 0, v[22:23]
	global_load_dwordx4 v[60:63], v[20:21], off
	v_sub_u32_e32 v20, v30, v31
	v_lshlrev_b32_e32 v20, v26, v31
	v_sub_u32_e32 v20, v30, v20
	v_lshl_add_u32 v20, v20, 5, v3
	v_lshlrev_b32_e32 v20, v27, v20
	v_lshl_add_u32 v20, v31, 7, v20
	v_add_u32_e32 v20, v20, v4
	v_add_co_u32_e32 v10, vcc, v28, v20
	s_nop 1
	v_addc_co_u32_e32 v11, vcc, 0, v29, vcc
	v_add_u32_e32 v21, 3, v27
	v_lshlrev_b32_e64 v12, v21, 1
	v_mov_b32_e32 v13, 0
	global_load_dword v7, v1, s[96:97] offset:4
	global_load_dword v8, v1, s[96:97] offset:8
	global_load_dword v9, v1, s[96:97] offset:12
	global_load_dword v18, v1, s[96:97] offset:16
.Ltr_loop:
	s_add_i32 s0, s0, s1
	s_cmp_lt_u32 s0, s9
	s_cbranch_scc0 .Ltr_last_x0
	s_cmpk_lt_u32 s0, 0x400
	s_cbranch_scc0 .Ltr_c1_x0
	v_mov_b32_e32 v30, s0
	v_mov_b32_e32 v24, s12
	v_mov_b32_e32 v25, s13
	v_mov_b32_e32 v26, 6
	v_mov_b32_e32 v27, 11
	v_mov_b32_e32 v28, s6
	v_mov_b32_e32 v29, s7
	s_branch .Ltr_go_x0

.Ltr_go_x0:
	v_lshrrev_b32_e32 v31, v26, v30
	v_lshlrev_b32_e32 v20, v26, v31
	v_sub_u32_e32 v20, v30, v20
	v_add_u32_e32 v21, 13, v26
	v_lshlrev_b32_e32 v21, v21, v31
	v_lshl_add_u32 v21, v20, 7, v21
	v_add_u32_e32 v22, 7, v26
	v_lshlrev_b32_e32 v23, v22, v3
	v_add3_u32 v21, v21, v23, v4
	v_add_co_u32_e32 v20, vcc, v24, v21
	s_nop 1
	v_addc_co_u32_e32 v21, vcc, 0, v25, vcc
	v_add_u32_e32 v22, 3, v22
	v_lshlrev_b32_e64 v22, v22, 1
	v_mov_b32_e32 v23, 0
	global_load_dwordx4 v[64:67], v[20:21], off
	v_lshl_add_u64 v[20:21], v[20:21], 0, v[22:23]
	global_load_dwordx4 v[68:71], v[20:21], off
	v_lshl_add_u64 v[20:21], v[20:21], 0, v[22:23]
	global_load_dwordx4 v[72:75], v[20:21], off
	v_lshl_add_u64 v[20:21], v[20:21], 0, v[22:23]
	global_load_dwordx4 v[76:79], v[20:21], off
	v_lshl_add_u64 v[20:21], v[20:21], 0, v[22:23]
	global_load_dwordx4 v[80:83], v[20:21], off
	v_lshl_add_u64 v[20:21], v[20:21], 0, v[22:23]
	global_load_dwordx4 v[84:87], v[20:21], off
	v_lshl_add_u64 v[20:21], v[20:21], 0, v[22:23]
	global_load_dwordx4 v[88:91], v[20:21], off
	v_lshl_add_u64 v[20:21], v[20:21], 0, v[22:23]
	global_load_dwordx4 v[92:95], v[20:21], off
	v_sub_u32_e32 v20, v30, v31
	v_lshlrev_b32_e32 v20, v26, v31
	v_sub_u32_e32 v20, v30, v20
	v_lshl_add_u32 v20, v20, 5, v3
	v_lshlrev_b32_e32 v20, v27, v20
	v_lshl_add_u32 v20, v31, 7, v20
	v_add_u32_e32 v20, v20, v4
	v_add_co_u32_e32 v14, vcc, v28, v20
	s_nop 1
	v_addc_co_u32_e32 v15, vcc, 0, v29, vcc
	v_add_u32_e32 v21, 3, v27
	v_lshlrev_b32_e64 v16, v21, 1
	v_mov_b32_e32 v17, 0
	s_waitcnt vmcnt(12)
	ds_write_b32 v5, v32
	ds_write_b32 v5, v33 offset:4
	ds_write_b32 v5, v34 offset:8
	ds_write_b32 v5, v35 offset:12
	ds_write_b32 v5, v36 offset:1056
	ds_write_b32 v5, v37 offset:1060
	ds_write_b32 v5, v38 offset:1064
	ds_write_b32 v5, v39 offset:1068
	ds_write_b32 v5, v40 offset:2112
	ds_write_b32 v5, v41 offset:2116
	ds_write_b32 v5, v42 offset:2120
	ds_write_b32 v5, v43 offset:2124
	ds_write_b32 v5, v44 offset:3168
	ds_write_b32 v5, v45 offset:3172
	ds_write_b32 v5, v46 offset:3176
	ds_write_b32 v5, v47 offset:3180
	ds_write_b32 v5, v48 offset:4224
	ds_write_b32 v5, v49 offset:4228
	ds_write_b32 v5, v50 offset:4232
	ds_write_b32 v5, v51 offset:4236
	ds_write_b32 v5, v52 offset:5280
	ds_write_b32 v5, v53 offset:5284
	ds_write_b32 v5, v54 offset:5288
	ds_write_b32 v5, v55 offset:5292
	ds_write_b32 v5, v56 offset:6336
	ds_write_b32 v5, v57 offset:6340
	ds_write_b32 v5, v58 offset:6344
	ds_write_b32 v5, v59 offset:6348
	ds_write_b32 v5, v60 offset:7392
	ds_write_b32 v5, v61 offset:7396
	ds_write_b32 v5, v62 offset:7400
	ds_write_b32 v5, v63 offset:7404
	s_waitcnt lgkmcnt(0)
	ds_read2_b32 v[96:97], v6 offset0:0 offset1:33
	ds_read2_b32 v[98:99], v6 offset0:66 offset1:99
	ds_read2_b32 v[100:101], v6 offset0:132 offset1:165
	ds_read2_b32 v[102:103], v6 offset0:198 offset1:231
	ds_read2_b32 v[104:105], v6 offset0:8 offset1:41
	ds_read2_b32 v[106:107], v6 offset0:74 offset1:107
	ds_read2_b32 v[108:109], v6 offset0:140 offset1:173
	ds_read2_b32 v[110:111], v6 offset0:206 offset1:239
	ds_read2_b32 v[112:113], v6 offset0:16 offset1:49
	ds_read2_b32 v[114:115], v6 offset0:82 offset1:115
	ds_read2_b32 v[116:117], v6 offset0:148 offset1:181
	ds_read2_b32 v[118:119], v6 offset0:214 offset1:247
	ds_read2_b32 v[120:121], v6 offset0:24 offset1:57
	ds_read2_b32 v[122:123], v6 offset0:90 offset1:123
	ds_read2_b32 v[124:125], v6 offset0:156 offset1:189
	ds_read2_b32 v[126:127], v6 offset0:222 offset1:255
	s_waitcnt lgkmcnt(0)
	v_cvt_pk_bf16_f32 v128, v96, v97
	v_cvt_pk_bf16_f32 v129, v98, v99
	v_cvt_pk_bf16_f32 v130, v100, v101
	v_cvt_pk_bf16_f32 v131, v102, v103
	global_store_dwordx4 v[10:11], v[128:131], off
	v_lshl_add_u64 v[10:11], v[10:11], 0, v[12:13]
	v_cvt_pk_bf16_f32 v132, v104, v105
	v_cvt_pk_bf16_f32 v133, v106, v107
	v_cvt_pk_bf16_f32 v134, v108, v109
	v_cvt_pk_bf16_f32 v135, v110, v111
	global_store_dwordx4 v[10:11], v[132:135], off
	v_lshl_add_u64 v[10:11], v[10:11], 0, v[12:13]
	v_cvt_pk_bf16_f32 v136, v112, v113
	v_cvt_pk_bf16_f32 v137, v114, v115
	v_cvt_pk_bf16_f32 v138, v116, v117
	v_cvt_pk_bf16_f32 v139, v118, v119
	global_store_dwordx4 v[10:11], v[136:139], off
	v_lshl_add_u64 v[10:11], v[10:11], 0, v[12:13]
	v_cvt_pk_bf16_f32 v140, v120, v121
	v_cvt_pk_bf16_f32 v141, v122, v123
	v_cvt_pk_bf16_f32 v142, v124, v125
	v_cvt_pk_bf16_f32 v143, v126, v127
	global_store_dwordx4 v[10:11], v[140:143], off
	s_branch .Ltr_cont_x0
.Ltr_last_x0:
	s_waitcnt vmcnt(4)
	ds_write_b32 v5, v32
	ds_write_b32 v5, v33 offset:4
	ds_write_b32 v5, v34 offset:8
	ds_write_b32 v5, v35 offset:12
	ds_write_b32 v5, v36 offset:1056
	ds_write_b32 v5, v37 offset:1060
	ds_write_b32 v5, v38 offset:1064
	ds_write_b32 v5, v39 offset:1068
	ds_write_b32 v5, v40 offset:2112
	ds_write_b32 v5, v41 offset:2116
	ds_write_b32 v5, v42 offset:2120
	ds_write_b32 v5, v43 offset:2124
	ds_write_b32 v5, v44 offset:3168
	ds_write_b32 v5, v45 offset:3172
	ds_write_b32 v5, v46 offset:3176
	ds_write_b32 v5, v47 offset:3180
	ds_write_b32 v5, v48 offset:4224
	ds_write_b32 v5, v49 offset:4228
	ds_write_b32 v5, v50 offset:4232
	ds_write_b32 v5, v51 offset:4236
	ds_write_b32 v5, v52 offset:5280
	ds_write_b32 v5, v53 offset:5284
	ds_write_b32 v5, v54 offset:5288
	ds_write_b32 v5, v55 offset:5292
	ds_write_b32 v5, v56 offset:6336
	ds_write_b32 v5, v57 offset:6340
	ds_write_b32 v5, v58 offset:6344
	ds_write_b32 v5, v59 offset:6348
	ds_write_b32 v5, v60 offset:7392
	ds_write_b32 v5, v61 offset:7396
	ds_write_b32 v5, v62 offset:7400
	ds_write_b32 v5, v63 offset:7404
	s_waitcnt lgkmcnt(0)
	ds_read2_b32 v[96:97], v6 offset0:0 offset1:33
	ds_read2_b32 v[98:99], v6 offset0:66 offset1:99
	ds_read2_b32 v[100:101], v6 offset0:132 offset1:165
	ds_read2_b32 v[102:103], v6 offset0:198 offset1:231
	ds_read2_b32 v[104:105], v6 offset0:8 offset1:41
	ds_read2_b32 v[106:107], v6 offset0:74 offset1:107
	ds_read2_b32 v[108:109], v6 offset0:140 offset1:173
	ds_read2_b32 v[110:111], v6 offset0:206 offset1:239
	ds_read2_b32 v[112:113], v6 offset0:16 offset1:49
	ds_read2_b32 v[114:115], v6 offset0:82 offset1:115
	ds_read2_b32 v[116:117], v6 offset0:148 offset1:181
	ds_read2_b32 v[118:119], v6 offset0:214 offset1:247
	ds_read2_b32 v[120:121], v6 offset0:24 offset1:57
	ds_read2_b32 v[122:123], v6 offset0:90 offset1:123
	ds_read2_b32 v[124:125], v6 offset0:156 offset1:189
	ds_read2_b32 v[126:127], v6 offset0:222 offset1:255
	s_waitcnt lgkmcnt(0)
	v_cvt_pk_bf16_f32 v128, v96, v97
	v_cvt_pk_bf16_f32 v129, v98, v99
	v_cvt_pk_bf16_f32 v130, v100, v101
	v_cvt_pk_bf16_f32 v131, v102, v103
	global_store_dwordx4 v[10:11], v[128:131], off
	v_lshl_add_u64 v[10:11], v[10:11], 0, v[12:13]
	v_cvt_pk_bf16_f32 v132, v104, v105
	v_cvt_pk_bf16_f32 v133, v106, v107
	v_cvt_pk_bf16_f32 v134, v108, v109
	v_cvt_pk_bf16_f32 v135, v110, v111
	global_store_dwordx4 v[10:11], v[132:135], off
	v_lshl_add_u64 v[10:11], v[10:11], 0, v[12:13]
	v_cvt_pk_bf16_f32 v136, v112, v113
	v_cvt_pk_bf16_f32 v137, v114, v115
	v_cvt_pk_bf16_f32 v138, v116, v117
	v_cvt_pk_bf16_f32 v139, v118, v119
	global_store_dwordx4 v[10:11], v[136:139], off
	v_lshl_add_u64 v[10:11], v[10:11], 0, v[12:13]
	v_cvt_pk_bf16_f32 v140, v120, v121
	v_cvt_pk_bf16_f32 v141, v122, v123
	v_cvt_pk_bf16_f32 v142, v124, v125
	v_cvt_pk_bf16_f32 v143, v126, v127
	global_store_dwordx4 v[10:11], v[140:143], off
	s_branch .Ltr_done

.Ltr_go_x1:
	v_lshrrev_b32_e32 v31, v26, v30
	v_lshlrev_b32_e32 v20, v26, v31
	v_sub_u32_e32 v20, v30, v20
	v_add_u32_e32 v21, 13, v26
	v_lshlrev_b32_e32 v21, v21, v31
	v_lshl_add_u32 v21, v20, 7, v21
	v_add_u32_e32 v22, 7, v26
	v_lshlrev_b32_e32 v23, v22, v3
	v_add3_u32 v21, v21, v23, v4
	v_add_co_u32_e32 v20, vcc, v24, v21
	s_nop 1
	v_addc_co_u32_e32 v21, vcc, 0, v25, vcc
	v_add_u32_e32 v22, 3, v22
	v_lshlrev_b32_e64 v22, v22, 1
	v_mov_b32_e32 v23, 0
	global_load_dwordx4 v[32:35], v[20:21], off
	v_lshl_add_u64 v[20:21], v[20:21], 0, v[22:23]
	global_load_dwordx4 v[36:39], v[20:21], off
	v_lshl_add_u64 v[20:21], v[20:21], 0, v[22:23]
	global_load_dwordx4 v[40:43], v[20:21], off
	v_lshl_add_u64 v[20:21], v[20:21], 0, v[22:23]
	global_load_dwordx4 v[44:47], v[20:21], off
	v_lshl_add_u64 v[20:21], v[20:21], 0, v[22:23]
	global_load_dwordx4 v[48:51], v[20:21], off
	v_lshl_add_u64 v[20:21], v[20:21], 0, v[22:23]
	global_load_dwordx4 v[52:55], v[20:21], off
	v_lshl_add_u64 v[20:21], v[20:21], 0, v[22:23]
	global_load_dwordx4 v[56:59], v[20:21], off
	v_lshl_add_u64 v[20:21], v[20:21], 0, v[22:23]
	global_load_dwordx4 v[60:63], v[20:21], off
	v_sub_u32_e32 v20, v30, v31
	v_lshlrev_b32_e32 v20, v26, v31
	v_sub_u32_e32 v20, v30, v20
	v_lshl_add_u32 v20, v20, 5, v3
	v_lshlrev_b32_e32 v20, v27, v20
	v_lshl_add_u32 v20, v31, 7, v20
	v_add_u32_e32 v20, v20, v4
	v_add_co_u32_e32 v10, vcc, v28, v20
	s_nop 1
	v_addc_co_u32_e32 v11, vcc, 0, v29, vcc
	v_add_u32_e32 v21, 3, v27
	v_lshlrev_b32_e64 v12, v21, 1
	v_mov_b32_e32 v13, 0
	s_waitcnt vmcnt(12)
	ds_write_b32 v5, v64
	ds_write_b32 v5, v65 offset:4
	ds_write_b32 v5, v66 offset:8
	ds_write_b32 v5, v67 offset:12
	ds_write_b32 v5, v68 offset:1056
	ds_write_b32 v5, v69 offset:1060
	ds_write_b32 v5, v70 offset:1064
	ds_write_b32 v5, v71 offset:1068
	ds_write_b32 v5, v72 offset:2112
	ds_write_b32 v5, v73 offset:2116
	ds_write_b32 v5, v74 offset:2120
	ds_write_b32 v5, v75 offset:2124
	ds_write_b32 v5, v76 offset:3168
	ds_write_b32 v5, v77 offset:3172
	ds_write_b32 v5, v78 offset:3176
	ds_write_b32 v5, v79 offset:3180
	ds_write_b32 v5, v80 offset:4224
	ds_write_b32 v5, v81 offset:4228
	ds_write_b32 v5, v82 offset:4232
	ds_write_b32 v5, v83 offset:4236
	ds_write_b32 v5, v84 offset:5280
	ds_write_b32 v5, v85 offset:5284
	ds_write_b32 v5, v86 offset:5288
	ds_write_b32 v5, v87 offset:5292
	ds_write_b32 v5, v88 offset:6336
	ds_write_b32 v5, v89 offset:6340
	ds_write_b32 v5, v90 offset:6344
	ds_write_b32 v5, v91 offset:6348
	ds_write_b32 v5, v92 offset:7392
	ds_write_b32 v5, v93 offset:7396
	ds_write_b32 v5, v94 offset:7400
	ds_write_b32 v5, v95 offset:7404
	s_waitcnt lgkmcnt(0)
	ds_read2_b32 v[96:97], v6 offset0:0 offset1:33
	ds_read2_b32 v[98:99], v6 offset0:66 offset1:99
	ds_read2_b32 v[100:101], v6 offset0:132 offset1:165
	ds_read2_b32 v[102:103], v6 offset0:198 offset1:231
	ds_read2_b32 v[104:105], v6 offset0:8 offset1:41
	ds_read2_b32 v[106:107], v6 offset0:74 offset1:107
	ds_read2_b32 v[108:109], v6 offset0:140 offset1:173
	ds_read2_b32 v[110:111], v6 offset0:206 offset1:239
	ds_read2_b32 v[112:113], v6 offset0:16 offset1:49
	ds_read2_b32 v[114:115], v6 offset0:82 offset1:115
	ds_read2_b32 v[116:117], v6 offset0:148 offset1:181
	ds_read2_b32 v[118:119], v6 offset0:214 offset1:247
	ds_read2_b32 v[120:121], v6 offset0:24 offset1:57
	ds_read2_b32 v[122:123], v6 offset0:90 offset1:123
	ds_read2_b32 v[124:125], v6 offset0:156 offset1:189
	ds_read2_b32 v[126:127], v6 offset0:222 offset1:255
	s_waitcnt lgkmcnt(0)
	v_cvt_pk_bf16_f32 v128, v96, v97
	v_cvt_pk_bf16_f32 v129, v98, v99
	v_cvt_pk_bf16_f32 v130, v100, v101
	v_cvt_pk_bf16_f32 v131, v102, v103
	global_store_dwordx4 v[14:15], v[128:131], off
	v_lshl_add_u64 v[14:15], v[14:15], 0, v[16:17]
	v_cvt_pk_bf16_f32 v132, v104, v105
	v_cvt_pk_bf16_f32 v133, v106, v107
	v_cvt_pk_bf16_f32 v134, v108, v109
	v_cvt_pk_bf16_f32 v135, v110, v111
	global_store_dwordx4 v[14:15], v[132:135], off
	v_lshl_add_u64 v[14:15], v[14:15], 0, v[16:17]
	v_cvt_pk_bf16_f32 v136, v112, v113
	v_cvt_pk_bf16_f32 v137, v114, v115
	v_cvt_pk_bf16_f32 v138, v116, v117
	v_cvt_pk_bf16_f32 v139, v118, v119
	global_store_dwordx4 v[14:15], v[136:139], off
	v_lshl_add_u64 v[14:15], v[14:15], 0, v[16:17]
	v_cvt_pk_bf16_f32 v140, v120, v121
	v_cvt_pk_bf16_f32 v141, v122, v123
	v_cvt_pk_bf16_f32 v142, v124, v125
	v_cvt_pk_bf16_f32 v143, v126, v127
	global_store_dwordx4 v[14:15], v[140:143], off
	s_branch .Ltr_loop
.Ltr_last_x1:
	s_waitcnt vmcnt(4)
	ds_write_b32 v5, v64
	ds_write_b32 v5, v65 offset:4
	ds_write_b32 v5, v66 offset:8
	ds_write_b32 v5, v67 offset:12
	ds_write_b32 v5, v68 offset:1056
	ds_write_b32 v5, v69 offset:1060
	ds_write_b32 v5, v70 offset:1064
	ds_write_b32 v5, v71 offset:1068
	ds_write_b32 v5, v72 offset:2112
	ds_write_b32 v5, v73 offset:2116
	ds_write_b32 v5, v74 offset:2120
	ds_write_b32 v5, v75 offset:2124
	ds_write_b32 v5, v76 offset:3168
	ds_write_b32 v5, v77 offset:3172
	ds_write_b32 v5, v78 offset:3176
	ds_write_b32 v5, v79 offset:3180
	ds_write_b32 v5, v80 offset:4224
	ds_write_b32 v5, v81 offset:4228
	ds_write_b32 v5, v82 offset:4232
	ds_write_b32 v5, v83 offset:4236
	ds_write_b32 v5, v84 offset:5280
	ds_write_b32 v5, v85 offset:5284
	ds_write_b32 v5, v86 offset:5288
	ds_write_b32 v5, v87 offset:5292
	ds_write_b32 v5, v88 offset:6336
	ds_write_b32 v5, v89 offset:6340
	ds_write_b32 v5, v90 offset:6344
	ds_write_b32 v5, v91 offset:6348
	ds_write_b32 v5, v92 offset:7392
	ds_write_b32 v5, v93 offset:7396
	ds_write_b32 v5, v94 offset:7400
	ds_write_b32 v5, v95 offset:7404
	s_waitcnt lgkmcnt(0)
	ds_read2_b32 v[96:97], v6 offset0:0 offset1:33
	ds_read2_b32 v[98:99], v6 offset0:66 offset1:99
	ds_read2_b32 v[100:101], v6 offset0:132 offset1:165
	ds_read2_b32 v[102:103], v6 offset0:198 offset1:231
	ds_read2_b32 v[104:105], v6 offset0:8 offset1:41
	ds_read2_b32 v[106:107], v6 offset0:74 offset1:107
	ds_read2_b32 v[108:109], v6 offset0:140 offset1:173
	ds_read2_b32 v[110:111], v6 offset0:206 offset1:239
	ds_read2_b32 v[112:113], v6 offset0:16 offset1:49
	ds_read2_b32 v[114:115], v6 offset0:82 offset1:115
	ds_read2_b32 v[116:117], v6 offset0:148 offset1:181
	ds_read2_b32 v[118:119], v6 offset0:214 offset1:247
	ds_read2_b32 v[120:121], v6 offset0:24 offset1:57
	ds_read2_b32 v[122:123], v6 offset0:90 offset1:123
	ds_read2_b32 v[124:125], v6 offset0:156 offset1:189
	ds_read2_b32 v[126:127], v6 offset0:222 offset1:255
	s_waitcnt lgkmcnt(0)
	v_cvt_pk_bf16_f32 v128, v96, v97
	v_cvt_pk_bf16_f32 v129, v98, v99
	v_cvt_pk_bf16_f32 v130, v100, v101
	v_cvt_pk_bf16_f32 v131, v102, v103
	global_store_dwordx4 v[14:15], v[128:131], off
	v_lshl_add_u64 v[14:15], v[14:15], 0, v[16:17]
	v_cvt_pk_bf16_f32 v132, v104, v105
	v_cvt_pk_bf16_f32 v133, v106, v107
	v_cvt_pk_bf16_f32 v134, v108, v109
	v_cvt_pk_bf16_f32 v135, v110, v111
	global_store_dwordx4 v[14:15], v[132:135], off
	v_lshl_add_u64 v[14:15], v[14:15], 0, v[16:17]
	v_cvt_pk_bf16_f32 v136, v112, v113
	v_cvt_pk_bf16_f32 v137, v114, v115
	v_cvt_pk_bf16_f32 v138, v116, v117
	v_cvt_pk_bf16_f32 v139, v118, v119
	global_store_dwordx4 v[14:15], v[136:139], off
	v_lshl_add_u64 v[14:15], v[14:15], 0, v[16:17]
	v_cvt_pk_bf16_f32 v140, v120, v121
	v_cvt_pk_bf16_f32 v141, v122, v123
	v_cvt_pk_bf16_f32 v142, v124, v125
	v_cvt_pk_bf16_f32 v143, v126, v127
	global_store_dwordx4 v[14:15], v[140:143], off
	s_branch .Ltr_done
.Ltr_done:
.LBB0_45:
	s_barrier
	global_load_dwordx2 v[2:3], v1, s[96:97] offset:80 sc0
	global_load_dwordx2 v[4:5], v1, s[96:97] offset:88 sc0
	global_load_dwordx2 v[6:7], v1, s[96:97] offset:16 sc0
	global_load_dwordx2 v[8:9], v1, s[96:97] offset:56 sc0
	s_and_b32 s0, s93, 0xffffffc0
	v_readlane_b32 s1, v246, 6
	s_cmpk_gt_i32 s1, 0xbf
	v_add_u32_e32 v160, s0, v163
	s_waitcnt vmcnt(3)
	v_readfirstlane_b32 s1, v3
	v_readfirstlane_b32 s0, v2
	s_waitcnt vmcnt(2)
	v_readfirstlane_b32 s13, v5
	v_readfirstlane_b32 s12, v4
	s_waitcnt vmcnt(1)
	v_readfirstlane_b32 s19, v7
	v_readfirstlane_b32 s18, v6
	s_waitcnt vmcnt(0)
	v_readfirstlane_b32 s15, v9
	v_readfirstlane_b32 s14, v8
	s_cbranch_scc1 .LBB0_55
	s_movk_i32 s9, 0x1400
	v_cmp_gt_i32_e32 vcc, s9, v160
	s_and_saveexec_b64 s[16:17], vcc
	s_cbranch_execz .LBB0_49
	s_lshl_b32 s9, s94, 8
	v_ashrrev_i32_e32 v161, 31, v160
	s_add_i32 s9, s9, 0
	s_movk_i32 s20, 0xc000
	v_lshl_add_u64 v[0:1], v[160:161], 2, s[18:19]
	v_lshl_add_u32 v4, v163, 2, s9
	s_mov_b64 s[18:19], 0
	s_movk_i32 s9, 0x1000
	v_mov_b32_e32 v3, 0
	s_mov_b32 s21, -1
	s_mov_b64 s[22:23], 0x800
	s_movk_i32 s24, 0x11ff
	v_mov_b32_e32 v2, v160
	s_mov_b64 s[18:19], 0x1000
	v_lshlrev_b32_e32 v8, 2, v2
	global_load_dword v20, v[0:1], off
	global_load_dword v21, v[0:1], off offset:2048
	v_lshl_add_u64 v[6:7], v[0:1], 0, s[18:19]
	global_load_dword v22, v[6:7], off
	global_load_dword v23, v[6:7], off offset:2048
	v_lshl_add_u64 v[6:7], v[6:7], 0, s[18:19]
	global_load_dword v24, v[6:7], off
	global_load_dword v25, v[6:7], off offset:2048
	v_lshl_add_u64 v[6:7], v[6:7], 0, s[18:19]
	global_load_dword v26, v[6:7], off
	global_load_dword v27, v[6:7], off offset:2048
	global_load_dword v28, v8, s[14:15]
	global_load_dword v29, v8, s[14:15] offset:2048
	s_waitcnt vmcnt(0) lgkmcnt(0)
	v_mul_f32_e32 v30, 0xbfb8aa3b, v20
	v_exp_f32_e32 v30, v30
	s_nop 0
	v_add_f32_e32 v30, 1.0, v30
	v_div_scale_f32 v31, s[26:27], v30, v30, 1.0
	v_rcp_f32_e32 v32, v31
	v_div_scale_f32 v33, vcc, 1.0, v30, 1.0
	v_fma_f32 v34, -v31, v32, 1.0
	v_fmac_f32_e32 v32, v34, v32
	v_mul_f32_e32 v34, v33, v32
	v_fma_f32 v35, -v31, v34, v33
	v_fmac_f32_e32 v34, v35, v32
	v_fma_f32 v31, -v31, v34, v33
	v_div_fmas_f32 v31, v31, v32, v34
	v_div_fixup_f32 v30, v31, v30, 1.0
	v_mul_f32_e32 v20, v20, v30
	ds_write_b32 v4, v20
	v_mul_f32_e32 v38, 0xbfb8aa3b, v21
	v_exp_f32_e32 v38, v38
	s_nop 0
	v_add_f32_e32 v38, 1.0, v38
	v_div_scale_f32 v39, s[26:27], v38, v38, 1.0
	v_rcp_f32_e32 v40, v39
	v_div_scale_f32 v41, vcc, 1.0, v38, 1.0
	v_fma_f32 v42, -v39, v40, 1.0
	v_fmac_f32_e32 v40, v42, v40
	v_mul_f32_e32 v42, v41, v40
	v_fma_f32 v43, -v39, v42, v41
	v_fmac_f32_e32 v42, v43, v40
	v_fma_f32 v39, -v39, v42, v41
	v_div_fmas_f32 v39, v39, v40, v42
	v_div_fixup_f32 v38, v39, v38, 1.0
	v_mul_f32_e32 v21, v21, v38
	ds_write_b32 v4, v21 offset:2048
	v_mul_f32_e32 v46, 0xbfb8aa3b, v22
	v_exp_f32_e32 v46, v46
	s_nop 0
	v_add_f32_e32 v46, 1.0, v46
	v_div_scale_f32 v47, s[26:27], v46, v46, 1.0
	v_rcp_f32_e32 v48, v47
	v_div_scale_f32 v49, vcc, 1.0, v46, 1.0
	v_fma_f32 v50, -v47, v48, 1.0
	v_fmac_f32_e32 v48, v50, v48
	v_mul_f32_e32 v50, v49, v48
	v_fma_f32 v51, -v47, v50, v49
	v_fmac_f32_e32 v50, v51, v48
	v_fma_f32 v47, -v47, v50, v49
	v_div_fmas_f32 v47, v47, v48, v50
	v_div_fixup_f32 v46, v47, v46, 1.0
	v_mul_f32_e32 v22, v22, v46
	ds_write_b32 v4, v22 offset:4096
	v_mul_f32_e32 v54, 0xbfb8aa3b, v23
	v_exp_f32_e32 v54, v54
	s_nop 0
	v_add_f32_e32 v54, 1.0, v54
	v_div_scale_f32 v55, s[26:27], v54, v54, 1.0
	v_rcp_f32_e32 v56, v55
	v_div_scale_f32 v57, vcc, 1.0, v54, 1.0
	v_fma_f32 v58, -v55, v56, 1.0
	v_fmac_f32_e32 v56, v58, v56
	v_mul_f32_e32 v58, v57, v56
	v_fma_f32 v59, -v55, v58, v57
	v_fmac_f32_e32 v58, v59, v56
	v_fma_f32 v55, -v55, v58, v57
	v_div_fmas_f32 v55, v55, v56, v58
	v_div_fixup_f32 v54, v55, v54, 1.0
	v_mul_f32_e32 v23, v23, v54
	ds_write_b32 v4, v23 offset:6144
	v_mul_f32_e32 v62, 0xbfb8aa3b, v24
	v_exp_f32_e32 v62, v62
	s_nop 0
	v_add_f32_e32 v62, 1.0, v62
	v_div_scale_f32 v63, s[26:27], v62, v62, 1.0
	v_rcp_f32_e32 v64, v63
	v_div_scale_f32 v65, vcc, 1.0, v62, 1.0
	v_fma_f32 v66, -v63, v64, 1.0
	v_fmac_f32_e32 v64, v66, v64
	v_mul_f32_e32 v66, v65, v64
	v_fma_f32 v67, -v63, v66, v65
	v_fmac_f32_e32 v66, v67, v64
	v_fma_f32 v63, -v63, v66, v65
	v_div_fmas_f32 v63, v63, v64, v66
	v_div_fixup_f32 v62, v63, v62, 1.0
	v_mul_f32_e32 v24, v24, v62
	ds_write_b32 v4, v24 offset:8192
	v_mul_f32_e32 v70, 0xbfb8aa3b, v25
	v_exp_f32_e32 v70, v70
	s_nop 0
	v_add_f32_e32 v70, 1.0, v70
	v_div_scale_f32 v71, s[26:27], v70, v70, 1.0
	v_rcp_f32_e32 v72, v71
	v_div_scale_f32 v73, vcc, 1.0, v70, 1.0
	v_fma_f32 v74, -v71, v72, 1.0
	v_fmac_f32_e32 v72, v74, v72
	v_mul_f32_e32 v74, v73, v72
	v_fma_f32 v75, -v71, v74, v73
	v_fmac_f32_e32 v74, v75, v72
	v_fma_f32 v71, -v71, v74, v73
	v_div_fmas_f32 v71, v71, v72, v74
	v_div_fixup_f32 v70, v71, v70, 1.0
	v_mul_f32_e32 v25, v25, v70
	ds_write_b32 v4, v25 offset:10240
	v_mul_f32_e32 v78, 0xbfb8aa3b, v26
	v_exp_f32_e32 v78, v78
	s_nop 0
	v_add_f32_e32 v78, 1.0, v78
	v_div_scale_f32 v79, s[26:27], v78, v78, 1.0
	v_rcp_f32_e32 v80, v79
	v_div_scale_f32 v81, vcc, 1.0, v78, 1.0
	v_fma_f32 v82, -v79, v80, 1.0
	v_fmac_f32_e32 v80, v82, v80
	v_mul_f32_e32 v82, v81, v80
	v_fma_f32 v83, -v79, v82, v81
	v_fmac_f32_e32 v82, v83, v80
	v_fma_f32 v79, -v79, v82, v81
	v_div_fmas_f32 v79, v79, v80, v82
	v_div_fixup_f32 v78, v79, v78, 1.0
	v_mul_f32_e32 v26, v26, v78
	ds_write_b32 v4, v26 offset:12288
	v_mul_f32_e32 v86, 0xbfb8aa3b, v27
	v_exp_f32_e32 v86, v86
	s_nop 0
	v_add_f32_e32 v86, 1.0, v86
	v_div_scale_f32 v87, s[26:27], v86, v86, 1.0
	v_rcp_f32_e32 v88, v87
	v_div_scale_f32 v89, vcc, 1.0, v86, 1.0
	v_fma_f32 v90, -v87, v88, 1.0
	v_fmac_f32_e32 v88, v90, v88
	v_mul_f32_e32 v90, v89, v88
	v_fma_f32 v91, -v87, v90, v89
	v_fmac_f32_e32 v90, v91, v88
	v_fma_f32 v87, -v87, v90, v89
	v_div_fmas_f32 v87, v87, v88, v90
	v_div_fixup_f32 v86, v87, v86, 1.0
	v_mul_f32_e32 v27, v27, v86
	ds_write_b32 v4, v27 offset:14336
	v_mul_f32_e32 v94, 0xbfb8aa3b, v28
	v_exp_f32_e32 v94, v94
	s_nop 0
	v_add_f32_e32 v94, 1.0, v94
	v_div_scale_f32 v95, s[26:27], v94, v94, 1.0
	v_rcp_f32_e32 v96, v95
	v_div_scale_f32 v97, vcc, 1.0, v94, 1.0
	v_fma_f32 v98, -v95, v96, 1.0
	v_fmac_f32_e32 v96, v98, v96
	v_mul_f32_e32 v98, v97, v96
	v_fma_f32 v99, -v95, v98, v97
	v_fmac_f32_e32 v98, v99, v96
	v_fma_f32 v95, -v95, v98, v97
	v_div_fmas_f32 v95, v95, v96, v98
	v_div_fixup_f32 v94, v95, v94, 1.0
	v_mul_f32_e32 v28, v28, v94
	ds_write_b32 v4, v28 offset:16384
	v_mul_f32_e32 v102, 0xbfb8aa3b, v29
	v_exp_f32_e32 v102, v102
	s_nop 0
	v_add_f32_e32 v102, 1.0, v102
	v_div_scale_f32 v103, s[26:27], v102, v102, 1.0
	v_rcp_f32_e32 v104, v103
	v_div_scale_f32 v105, vcc, 1.0, v102, 1.0
	v_fma_f32 v106, -v103, v104, 1.0
	v_fmac_f32_e32 v104, v106, v104
	v_mul_f32_e32 v106, v105, v104
	v_fma_f32 v107, -v103, v106, v105
	v_fmac_f32_e32 v106, v107, v104
	v_fma_f32 v103, -v103, v106, v105
	v_div_fmas_f32 v103, v103, v104, v106
	v_div_fixup_f32 v102, v103, v102, 1.0
	v_mul_f32_e32 v29, v29, v102
	ds_write_b32 v4, v29 offset:18432
